# GEMM tile prologues: accumulator zeroing with v_mov_b64 pairs (64 instead of 128 moves per tile, 4 K-loops)
# speedup vs baseline: 1.0038x; 1.0006x over previous
.LBB0_52:
	s_ashr_i32 s43, s42, 31
	s_lshl_b64 s[16:17], s[42:43], 19
	s_add_u32 s44, s68, s16
	s_addc_u32 s45, s69, s17
	s_and_b64 s[16:17], s[40:41], exec
	s_cselect_b32 s15, s45, s51
	s_cselect_b32 s24, s44, s50
	s_ashr_i32 s13, s12, 31
	s_lshl_b64 s[16:17], s[12:13], 19
	s_add_u32 s46, s6, s16
	s_addc_u32 s47, s7, s17
	s_and_b64 s[16:17], s[40:41], exec
	s_cselect_b32 s13, s47, s53
	s_cselect_b32 s43, s46, s52
	s_add_u32 s50, s50, 0x40080
	s_addc_u32 s51, s51, 0
	s_add_u32 s49, s52, 0x100
	v_mov_b64_e32 v[0:1], 0
	s_addc_u32 s67, s53, 0
	s_mov_b32 s70, -2
	s_waitcnt lgkmcnt(0)
	v_mov_b64_e32 v[2:3], 0
	v_mov_b64_e32 v[4:5], 0
	v_mov_b64_e32 v[6:7], 0
	v_mov_b64_e32 v[16:17], 0
	v_mov_b64_e32 v[18:19], 0
	v_mov_b64_e32 v[22:23], 0
	v_mov_b64_e32 v[24:25], 0
	v_mov_b64_e32 v[34:35], 0
	v_mov_b64_e32 v[36:37], 0
	v_mov_b64_e32 v[38:39], 0
	v_mov_b64_e32 v[40:41], 0
	v_mov_b64_e32 v[50:51], 0
	v_mov_b64_e32 v[52:53], 0
	v_mov_b64_e32 v[54:55], 0
	v_mov_b64_e32 v[56:57], 0
	v_mov_b64_e32 v[8:9], 0
	v_mov_b64_e32 v[10:11], 0
	v_mov_b64_e32 v[12:13], 0
	v_mov_b64_e32 v[14:15], 0
	v_mov_b64_e32 v[26:27], 0
	v_mov_b64_e32 v[28:29], 0
	v_mov_b64_e32 v[30:31], 0
	v_mov_b64_e32 v[32:33], 0
	v_mov_b64_e32 v[42:43], 0
	v_mov_b64_e32 v[44:45], 0
	v_mov_b64_e32 v[46:47], 0
	v_mov_b64_e32 v[48:49], 0
	v_mov_b64_e32 v[58:59], 0
	v_mov_b64_e32 v[60:61], 0
	v_mov_b64_e32 v[62:63], 0
	v_mov_b64_e32 v[64:65], 0
	v_mov_b64_e32 v[66:67], 0
	v_mov_b64_e32 v[68:69], 0
	v_mov_b64_e32 v[70:71], 0
	v_mov_b64_e32 v[72:73], 0
	v_mov_b64_e32 v[82:83], 0
	v_mov_b64_e32 v[84:85], 0
	v_mov_b64_e32 v[86:87], 0
	v_mov_b64_e32 v[88:89], 0
	v_mov_b64_e32 v[98:99], 0
	v_mov_b64_e32 v[100:101], 0
	v_mov_b64_e32 v[102:103], 0
	v_mov_b64_e32 v[104:105], 0
	v_mov_b64_e32 v[114:115], 0
	v_mov_b64_e32 v[116:117], 0
	v_mov_b64_e32 v[118:119], 0
	v_mov_b64_e32 v[120:121], 0
	v_mov_b64_e32 v[74:75], 0
	v_mov_b64_e32 v[76:77], 0
	v_mov_b64_e32 v[78:79], 0
	v_mov_b64_e32 v[80:81], 0
	v_mov_b64_e32 v[90:91], 0
	v_mov_b64_e32 v[92:93], 0
	v_mov_b64_e32 v[94:95], 0
	v_mov_b64_e32 v[96:97], 0
	v_mov_b64_e32 v[106:107], 0
	v_mov_b64_e32 v[108:109], 0
	v_mov_b64_e32 v[110:111], 0
	v_mov_b64_e32 v[112:113], 0
	v_mov_b64_e32 v[122:123], 0
	v_mov_b64_e32 v[124:125], 0
	v_mov_b64_e32 v[126:127], 0
	v_mov_b64_e32 v[128:129], 0
	s_cmp_lg_u64 s[10:11], 0
	s_cbranch_scc1 .Lprio_skip_out
	s_setprio 1

.LBB0_1037:
	s_ashr_i32 s61, s60, 31
	s_lshl_b64 s[10:11], s[60:61], 19
	s_add_u32 s70, s18, s10
	s_addc_u32 s71, s19, s11
	s_and_b64 s[10:11], s[40:41], exec
	s_cselect_b32 s12, s71, s7
	s_cselect_b32 s13, s70, s6
	s_ashr_i32 s57, s56, 31
	s_lshl_b64 s[10:11], s[56:57], 19
	s_add_u32 s80, s58, s10
	s_addc_u32 s81, s59, s11
	s_and_b64 s[10:11], s[40:41], exec
	s_cselect_b32 s42, s81, s9
	s_cselect_b32 s43, s80, s8
	s_add_u32 s6, s6, 0x40080
	s_addc_u32 s7, s7, 0
	s_add_u32 s44, s8, 0x100
	v_mov_b64_e32 v[0:1], 0
	s_addc_u32 s45, s9, 0
	s_mov_b32 s46, -2
	v_mov_b64_e32 v[2:3], 0
	v_mov_b64_e32 v[4:5], 0
	v_mov_b64_e32 v[6:7], 0
	v_mov_b64_e32 v[16:17], 0
	v_mov_b64_e32 v[18:19], 0
	v_mov_b64_e32 v[22:23], 0
	v_mov_b64_e32 v[24:25], 0
	v_mov_b64_e32 v[34:35], 0
	v_mov_b64_e32 v[36:37], 0
	v_mov_b64_e32 v[38:39], 0
	v_mov_b64_e32 v[40:41], 0
	v_mov_b64_e32 v[50:51], 0
	v_mov_b64_e32 v[52:53], 0
	v_mov_b64_e32 v[54:55], 0
	v_mov_b64_e32 v[56:57], 0
	v_mov_b64_e32 v[8:9], 0
	v_mov_b64_e32 v[10:11], 0
	v_mov_b64_e32 v[12:13], 0
	v_mov_b64_e32 v[14:15], 0
	v_mov_b64_e32 v[26:27], 0
	v_mov_b64_e32 v[28:29], 0
	v_mov_b64_e32 v[30:31], 0
	v_mov_b64_e32 v[32:33], 0
	v_mov_b64_e32 v[42:43], 0
	v_mov_b64_e32 v[44:45], 0
	v_mov_b64_e32 v[46:47], 0
	v_mov_b64_e32 v[48:49], 0
	v_mov_b64_e32 v[58:59], 0
	v_mov_b64_e32 v[60:61], 0
	v_mov_b64_e32 v[62:63], 0
	v_mov_b64_e32 v[64:65], 0
	v_mov_b64_e32 v[66:67], 0
	v_mov_b64_e32 v[68:69], 0
	v_mov_b64_e32 v[70:71], 0
	v_mov_b64_e32 v[72:73], 0
	v_mov_b64_e32 v[82:83], 0
	v_mov_b64_e32 v[84:85], 0
	v_mov_b64_e32 v[86:87], 0
	v_mov_b64_e32 v[88:89], 0
	v_mov_b64_e32 v[98:99], 0
	v_mov_b64_e32 v[100:101], 0
	v_mov_b64_e32 v[102:103], 0
	v_mov_b64_e32 v[104:105], 0
	v_mov_b64_e32 v[114:115], 0
	v_mov_b64_e32 v[116:117], 0
	v_mov_b64_e32 v[118:119], 0
	v_mov_b64_e32 v[120:121], 0
	v_mov_b64_e32 v[74:75], 0
	v_mov_b64_e32 v[76:77], 0
	v_mov_b64_e32 v[78:79], 0
	v_mov_b64_e32 v[80:81], 0
	v_mov_b64_e32 v[90:91], 0
	v_mov_b64_e32 v[92:93], 0
	v_mov_b64_e32 v[94:95], 0
	v_mov_b64_e32 v[96:97], 0
	v_mov_b64_e32 v[106:107], 0
	v_mov_b64_e32 v[108:109], 0
	v_mov_b64_e32 v[110:111], 0
	v_mov_b64_e32 v[112:113], 0
	v_mov_b64_e32 v[122:123], 0
	v_mov_b64_e32 v[124:125], 0
	v_mov_b64_e32 v[126:127], 0
	v_mov_b64_e32 v[128:129], 0
	s_cmp_lg_u64 s[54:55], 0
	s_cbranch_scc1 .Lprio_skip_proj
	s_setprio 1

.LBB0_1597:
	s_ashr_i32 s11, s10, 31
	s_lshl_b64 s[12:13], s[10:11], 19
	s_add_u32 s12, s18, s12
	s_addc_u32 s13, s19, s13
	s_and_b64 s[16:17], s[40:41], exec
	s_cselect_b32 s11, s13, s43
	s_cselect_b32 s15, s12, s42
	s_ashr_i32 s9, s8, 31
	s_lshl_b64 s[16:17], s[8:9], 19
	s_add_u32 s46, s27, s16
	s_addc_u32 s47, s28, s17
	s_and_b64 s[16:17], s[40:41], exec
	s_cselect_b32 s9, s47, s49
	s_cselect_b32 s58, s46, s48
	s_add_u32 s42, s42, 0x40080
	s_addc_u32 s43, s43, 0
	s_add_u32 s59, s48, 0x100
	v_mov_b64_e32 v[8:9], 0
	s_addc_u32 s60, s49, 0
	s_mov_b32 s61, -2
	v_mov_b64_e32 v[10:11], 0
	v_mov_b64_e32 v[16:17], 0
	v_mov_b64_e32 v[18:19], 0
	v_mov_b64_e32 v[26:27], 0
	v_mov_b64_e32 v[28:29], 0
	v_mov_b64_e32 v[34:35], 0
	v_mov_b64_e32 v[36:37], 0
	v_mov_b64_e32 v[42:43], 0
	v_mov_b64_e32 v[44:45], 0
	v_mov_b64_e32 v[50:51], 0
	v_mov_b64_e32 v[52:53], 0
	v_mov_b64_e32 v[58:59], 0
	v_mov_b64_e32 v[60:61], 0
	v_mov_b64_e32 v[66:67], 0
	v_mov_b64_e32 v[68:69], 0
	v_mov_b64_e32 v[12:13], 0
	v_mov_b64_e32 v[14:15], 0
	v_mov_b64_e32 v[22:23], 0
	v_mov_b64_e32 v[24:25], 0
	v_mov_b64_e32 v[30:31], 0
	v_mov_b64_e32 v[32:33], 0
	v_mov_b64_e32 v[38:39], 0
	v_mov_b64_e32 v[40:41], 0
	v_mov_b64_e32 v[46:47], 0
	v_mov_b64_e32 v[48:49], 0
	v_mov_b64_e32 v[54:55], 0
	v_mov_b64_e32 v[56:57], 0
	v_mov_b64_e32 v[62:63], 0
	v_mov_b64_e32 v[64:65], 0
	v_mov_b64_e32 v[70:71], 0
	v_mov_b64_e32 v[72:73], 0
	v_mov_b64_e32 v[74:75], 0
	v_mov_b64_e32 v[76:77], 0
	v_mov_b64_e32 v[82:83], 0
	v_mov_b64_e32 v[84:85], 0
	v_mov_b64_e32 v[90:91], 0
	v_mov_b64_e32 v[92:93], 0
	v_mov_b64_e32 v[98:99], 0
	v_mov_b64_e32 v[100:101], 0
	v_mov_b64_e32 v[106:107], 0
	v_mov_b64_e32 v[108:109], 0
	v_mov_b64_e32 v[114:115], 0
	v_mov_b64_e32 v[116:117], 0
	v_mov_b64_e32 v[122:123], 0
	v_mov_b64_e32 v[124:125], 0
	v_mov_b64_e32 v[130:131], 0
	v_mov_b64_e32 v[132:133], 0
	v_mov_b64_e32 v[78:79], 0
	v_mov_b64_e32 v[80:81], 0
	v_mov_b64_e32 v[86:87], 0
	v_mov_b64_e32 v[88:89], 0
	v_mov_b64_e32 v[94:95], 0
	v_mov_b64_e32 v[96:97], 0
	v_mov_b64_e32 v[102:103], 0
	v_mov_b64_e32 v[104:105], 0
	v_mov_b64_e32 v[110:111], 0
	v_mov_b64_e32 v[112:113], 0
	v_mov_b64_e32 v[118:119], 0
	v_mov_b64_e32 v[120:121], 0
	v_mov_b64_e32 v[126:127], 0
	v_mov_b64_e32 v[128:129], 0
	v_mov_b64_e32 v[134:135], 0
	v_mov_b64_e32 v[136:137], 0
	s_cmp_lg_u64 s[6:7], 0
	s_cbranch_scc1 .Lprio_skip_gu
	s_setprio 1

.LBB0_2065:
	s_add_u32 s56, s26, 0x100
	v_mov_b64_e32 v[0:1], 0
	s_addc_u32 s57, s27, 0
	s_mov_b32 s58, -2
	s_waitcnt lgkmcnt(0)
	v_mov_b64_e32 v[2:3], 0
	v_mov_b64_e32 v[4:5], 0
	v_mov_b64_e32 v[6:7], 0
	v_mov_b64_e32 v[16:17], 0
	v_mov_b64_e32 v[18:19], 0
	v_mov_b64_e32 v[22:23], 0
	v_mov_b64_e32 v[24:25], 0
	v_mov_b64_e32 v[34:35], 0
	v_mov_b64_e32 v[36:37], 0
	v_mov_b64_e32 v[38:39], 0
	v_mov_b64_e32 v[40:41], 0
	v_mov_b64_e32 v[50:51], 0
	v_mov_b64_e32 v[52:53], 0
	v_mov_b64_e32 v[54:55], 0
	v_mov_b64_e32 v[56:57], 0
	v_mov_b64_e32 v[8:9], 0
	v_mov_b64_e32 v[10:11], 0
	v_mov_b64_e32 v[12:13], 0
	v_mov_b64_e32 v[14:15], 0
	v_mov_b64_e32 v[26:27], 0
	v_mov_b64_e32 v[28:29], 0
	v_mov_b64_e32 v[30:31], 0
	v_mov_b64_e32 v[32:33], 0
	v_mov_b64_e32 v[42:43], 0
	v_mov_b64_e32 v[44:45], 0
	v_mov_b64_e32 v[46:47], 0
	v_mov_b64_e32 v[48:49], 0
	v_mov_b64_e32 v[58:59], 0
	v_mov_b64_e32 v[60:61], 0
	v_mov_b64_e32 v[62:63], 0
	v_mov_b64_e32 v[64:65], 0
	v_mov_b64_e32 v[66:67], 0
	v_mov_b64_e32 v[68:69], 0
	v_mov_b64_e32 v[70:71], 0
	v_mov_b64_e32 v[72:73], 0
	v_mov_b64_e32 v[82:83], 0
	v_mov_b64_e32 v[84:85], 0
	v_mov_b64_e32 v[86:87], 0
	v_mov_b64_e32 v[88:89], 0
	v_mov_b64_e32 v[98:99], 0
	v_mov_b64_e32 v[100:101], 0
	v_mov_b64_e32 v[102:103], 0
	v_mov_b64_e32 v[104:105], 0
	v_mov_b64_e32 v[114:115], 0
	v_mov_b64_e32 v[116:117], 0
	v_mov_b64_e32 v[118:119], 0
	v_mov_b64_e32 v[120:121], 0
	v_mov_b64_e32 v[74:75], 0
	v_mov_b64_e32 v[76:77], 0
	v_mov_b64_e32 v[78:79], 0
	v_mov_b64_e32 v[80:81], 0
	v_mov_b64_e32 v[90:91], 0
	v_mov_b64_e32 v[92:93], 0
	v_mov_b64_e32 v[94:95], 0
	v_mov_b64_e32 v[96:97], 0
	v_mov_b64_e32 v[106:107], 0
	v_mov_b64_e32 v[108:109], 0
	v_mov_b64_e32 v[110:111], 0
	v_mov_b64_e32 v[112:113], 0
	v_mov_b64_e32 v[122:123], 0
	v_mov_b64_e32 v[124:125], 0
	v_mov_b64_e32 v[126:127], 0
	v_mov_b64_e32 v[128:129], 0
	s_cmp_lg_u64 s[8:9], 0
	s_cbranch_scc1 .Lprio_skip_down
	s_setprio 1
